# P2 work-queue fetch: the four flat (generic) accesses to the two LDS control words replaced by ds_read_b32 / ds_write_b32
# speedup vs baseline: 1.0136x; 1.0042x over previous
; DI void phase2(const Params& p, unsigned char* lds) {
;     ...
;         if (tid == 0) {
;             unsigned* heads = (unsigned*)(p.ws + OFF_XBAR + 15360);
;             const unsigned x0 = (unsigned)__builtin_amdgcn_s_getreg((3 << 11) | 20) & 7u;
;             unsigned k = sItem[1], it = 0xffffffffu;
;             while (k < 8u) {
;                 const unsigned x = (x0 + k) & 7u;
;                 const unsigned got = atomicAdd(heads + x, 1u);
;                 if (got < N_GLA + N_ATT) { it = got | (x << 16); break; }
;                 ++k;
;             }
;             sItem[1] = k; sItem[0] = it;
.LBB0_1800:
.LBB0_1801:
	s_and_saveexec_b64 s[4:5], s[40:41]
	s_cbranch_execz .LBB0_1809
	s_mov_b64 s[6:7], src_shared_base
	s_cmp_lg_u32 s42, -1
	s_cselect_b32 s6, s42, 0
	s_cselect_b32 s7, s7, 0
	s_waitcnt vmcnt(0)
	v_mov_b32_e32 v2, s6
	v_mov_b32_e32 v3, s7
	s_getreg_b32 s0, hwreg(HW_REG_XCC_ID, 0, 4)
	ds_read_b32 v3, v2
	s_waitcnt lgkmcnt(0)
	s_mov_b64 s[6:7], 0
	s_branch .LBB0_1804

; DI void attn_item(const Params& p, unsigned char* lds, int b, int hd, int qb, float lam) {
;     const int tid = opaque_tid(), lane = tid & 63, wave = tid >> 6, l31 = lane & 31, h = lane >> 5;
;     const int sub = wave >> 2, rt = wave & 3;
;     const bf16_t* aq = (const bf16_t*)((unsigned char*)p.out + DO_AQ);
;     const bf16_t* ak = (const bf16_t*)(p.ws + OFF_AK);
;     const bf16_t* avT = (const bf16_t*)(p.ws + OFF_AVT);
;     const bf16_t* akm = (const bf16_t*)(p.ws + OFF_AKM);
;     const bf16_t* avTm = (const bf16_t*)(p.ws + OFF_AVTM);
;     bf16_t* az = (bf16_t*)(p.ws + OFF_AZ);
;     const int qs = qb * 128 + rt * 32 + l31;
;     const size_t grow = (size_t)b * 4096 + qs;
;     bf16x8 qf[4];
; #pragma unroll
;     for (int ks = 0; ks < 4; ++ks) qf[ks] = *(const bf16x8*)(aq + grow * 1024 + hd * 128 + sub * 64 + ks * 16 + 8 * h);
;     f32x16 O[4];
; #pragma unroll
;     for (int d = 0; d < 4; ++d)
; #pragma unroll
;         for (int i = 0; i < 16; ++i) O[d][i] = 0.f;
;     float m = 0.f, l = 0.f;
;     const int T = 2 * qb + 3;
;     u32x4 k0r[2], v0r[2];
;     const int krow_ = tid >> 4, kc_ = tid & 15, vdv_ = tid >> 3, vc_ = tid & 7;
;     const bf16_t* kp = ak + ((size_t)b * 4096 + krow_) * 1024 + hd * 128 + kc_ * 8;
;     const bf16_t* vp_ = avT + ((size_t)(b * 8 + hd) * 128 + vdv_) * 4096 + vc_ * 8;
;     ...
;     {
;         const bf16_t* km_ = akm + (size_t)krow_ * 1024 + hd * 128 + kc_ * 8;
;         k0r[0] = *(const u32x4*)km_; k0r[1] = *(const u32x4*)(km_ + 32 * 1024);
;         const bf16_t* vm_ = avTm + (size_t)(hd * 128 + vdv_) * 64 + vc_ * 8;
;         v0r[0] = *(const u32x4*)vm_; v0r[1] = *(const u32x4*)(vm_ + 64 * 64);
;     }
;     u32x4 k1r[2], v1r[2];
;     A_LOAD_REAL(k1r, v1r);
; DI void phase2(const Params& p, unsigned char* lds) {
;     ...
;             sItem[1] = k; sItem[0] = it;
;         }
;         __syncthreads();
;         const unsigned item = (unsigned)__builtin_amdgcn_readfirstlane((int)sItem[0]);
;         __syncthreads();
;         if (item == 0xffffffffu) break;
;         const unsigned x = item >> 16, idx = item & 0xffffu;
;         if (idx < N_GLA) { const unsigned gi = x * N_GLA + idx; gla_item<GLA_DL>(p, lds, gi / (4 * NSL), (gi / NSL) & 3, gi % NSL); }
;         else { const unsigned a = idx - N_GLA, pair = 4 * x + ((a >> 2) & 3); attn_item(p, lds, pair & 3, pair >> 2, 31 - (int)(((a >> 4) << 2) + (a & 3)), lam); }
.LBB0_1806:
	s_or_b64 exec, exec, s[6:7]
	s_xor_b64 s[6:7], s[8:9], -1
	v_mov_b32_e32 v3, -1
	s_and_saveexec_b64 s[8:9], s[6:7]
	s_xor_b64 s[6:7], exec, s[8:9]
	v_lshl_or_b32 v3, v2, 16, v4
	s_or_b64 exec, exec, s[6:7]
	s_cmp_lg_u32 s42, -1
	s_mov_b64 s[6:7], src_shared_base
	s_cselect_b32 s0, s42, 0
	s_cselect_b32 s6, s7, 0
	v_mov_b32_e32 v4, s0
	s_add_i32 s0, 0, 0x25000
	s_cmp_lg_u32 s0, -1
	v_mov_b32_e32 v5, s6
	s_cselect_b32 s0, s0, 0
	s_cselect_b32 s6, s7, 0
	ds_write_b32 v4, v1
	v_mov_b32_e32 v4, s0
	v_mov_b32_e32 v5, s6
	ds_write_b32 v4, v3
	s_waitcnt lgkmcnt(0)
.LBB0_1809:
	s_or_b64 exec, exec, s[4:5]
	s_add_i32 s0, 0, 0x25000
	s_cmp_lg_u32 s0, -1
	s_cselect_b32 s0, s0, 0
	s_cselect_b32 s4, s57, 0
	s_waitcnt vmcnt(0)
	v_mov_b32_e32 v2, s0
	v_mov_b32_e32 v3, s4
	s_waitcnt lgkmcnt(0)
	s_barrier
	ds_read_b32 v1, v2
	s_waitcnt vmcnt(0) lgkmcnt(0)
	s_barrier
	v_readfirstlane_b32 s8, v1
	s_cmp_eq_u32 s8, -1
	s_cbranch_scc1 .LBB0_1823
	s_lshr_b32 s9, s8, 16
	s_and_b32 s0, s8, 0xffff
	s_cmp_gt_u32 s0, 7
	s_mov_b64 s[4:5], -1
	s_cbranch_scc0 .LBB0_1831
	s_add_i32 s4, s0, -8
	s_lshr_b32 s0, s4, 2
	s_and_b32 s0, s0, 0x3ffffffc
	s_and_b32 s5, s8, 3
	s_or_b32 s0, s0, s5
	v_mov_b32_e32 v132, v186
	s_sub_i32 s0, 31, s0
	s_lshl_b32 s6, s0, 7
	v_lshrrev_b32_e32 v1, 1, v132
	v_and_b32_e32 v146, 31, v132
	v_and_b32_e32 v148, 0x60, v1
	s_bfe_u32 s11, s4, 0x20002
	v_or3_b32 v138, v148, s6, v146
	s_lshl_b32 s54, s11, 12
	v_ashrrev_i32_e32 v139, 31, v138
	v_lshl_add_u64 v[2:3], v[138:139], 0, s[54:55]
	v_ashrrev_i32_e32 v147, 8, v132
	v_lshlrev_b64 v[136:137], 11, v[2:3]
	v_lshl_add_u64 v[2:3], s[68:69], 0, v[136:137]
	s_lshl_b32 s6, s9, 8
	s_mov_b32 s7, s55
	v_lshlrev_b32_e32 v4, 6, v147
	v_lshl_add_u64 v[2:3], v[2:3], 0, s[6:7]
	v_ashrrev_i32_e32 v5, 31, v4
	v_lshl_add_u64 v[2:3], v[4:5], 1, v[2:3]
	v_ashrrev_i32_e32 v4, 4, v132
	v_ashrrev_i32_e32 v5, 31, v4
	v_lshlrev_b64 v[12:13], 11, v[4:5]
	v_bfe_u32 v149, v132, 5, 1
	v_lshlrev_b32_e32 v1, 4, v132
	v_lshl_add_u64 v[12:13], s[64:65], 0, v[12:13]
	v_lshlrev_b32_e32 v98, 4, v149
	v_and_b32_e32 v140, 0xf0, v1
	v_mov_b32_e32 v141, v99
	v_lshl_add_u64 v[12:13], v[12:13], 0, s[6:7]
	v_lshl_add_u64 v[2:3], v[2:3], 0, v[98:99]
	v_lshl_add_u64 v[12:13], v[12:13], 0, v[140:141]
	global_load_dwordx4 v[100:103], v[2:3], off
	global_load_dwordx4 v[104:107], v[2:3], off offset:32
	global_load_dwordx4 v[108:111], v[2:3], off offset:64
	global_load_dwordx4 v[112:115], v[2:3], off offset:96
	global_load_dwordx4 v[116:119], v[12:13], off
	v_add_co_u32_e32 v2, vcc, s43, v12
	s_lshl_b32 s10, s9, 7
	v_ashrrev_i32_e32 v6, 3, v132
	v_addc_co_u32_e32 v3, vcc, 0, v13, vcc
	global_load_dwordx4 v[120:123], v[2:3], off
	v_add_u32_e32 v2, s10, v6
	v_ashrrev_i32_e32 v3, 31, v2
	v_lshlrev_b64 v[2:3], 7, v[2:3]
	v_and_b32_e32 v10, 0x70, v1
	v_mov_b32_e32 v11, v99
	v_lshl_add_u64 v[2:3], s[62:63], 0, v[2:3]
	v_lshl_add_u64 v[2:3], v[2:3], 0, v[10:11]
	global_load_dwordx4 v[124:127], v[2:3], off
	v_lshl_add_u64 v[8:9], v[4:5], 0, s[54:55]
	v_lshlrev_b64 v[8:9], 11, v[8:9]
	v_add_co_u32_e32 v2, vcc, s56, v2
	v_lshl_add_u64 v[8:9], s[44:45], 0, v[8:9]
	s_lshl_b32 s11, s11, 10
	v_addc_co_u32_e32 v3, vcc, 0, v3, vcc
	v_lshl_add_u64 v[8:9], v[8:9], 0, s[6:7]
	s_add_i32 s54, s11, s10
	v_ashrrev_i32_e32 v7, 31, v6
	global_load_dwordx4 v[128:131], v[2:3], off
	v_lshl_add_u64 v[82:83], v[8:9], 0, v[140:141]
	v_lshl_add_u64 v[8:9], v[6:7], 0, s[54:55]
	v_lshlrev_b64 v[8:9], 13, v[8:9]
	v_lshl_add_u64 v[8:9], s[60:61], 0, v[8:9]
	v_add_co_u32_e32 v2, vcc, s43, v82
	v_lshl_add_u64 v[84:85], v[8:9], 0, v[10:11]
	s_nop 0
	v_addc_co_u32_e32 v3, vcc, 0, v83, vcc
	v_add_co_u32_e32 v8, vcc, s74, v84
	global_load_dwordx4 v[74:77], v[82:83], off
	global_load_dwordx4 v[70:73], v[84:85], off
	v_addc_co_u32_e32 v9, vcc, 0, v85, vcc
	global_load_dwordx4 v[78:81], v[2:3], off
	global_load_dwordx4 v[66:69], v[8:9], off
	v_lshlrev_b32_e32 v2, 3, v132
	v_mul_lo_u32 v139, v4, s75
	v_add_u32_e32 v4, 0x200, v132
	v_and_b32_e32 v150, 0x60, v1
	v_and_b32_e32 v151, 8, v2
	v_lshrrev_b32_e32 v5, 4, v4
	v_add3_u32 v1, 0, v150, v151
	v_mul_lo_u32 v152, v6, s52
	v_add_u32_e32 v3, 0, v140
	v_mul_lo_u32 v141, v5, s75
	v_add_u32_e32 v97, v1, v152
	v_add_u32_e32 v87, v3, v139
	v_add_u32_e32 v96, v3, v141
	v_add_u32_e32 v2, 0x4000, v97
	s_waitcnt vmcnt(11)
	s_waitcnt vmcnt(10)
	s_waitcnt vmcnt(9)
	s_waitcnt vmcnt(8)
	s_waitcnt vmcnt(7)
	ds_write_b128 v87, v[116:119]
	v_mad_u32_u24 v42, v146, s75, 0
	v_lshl_or_b32 v154, v147, 7, v98
	s_waitcnt vmcnt(6)
	ds_write_b128 v96, v[120:123]
	s_waitcnt vmcnt(5)
	ds_write2_b64 v2, v[124:125], v[126:127] offset0:128 offset1:130
	v_lshrrev_b32_e32 v2, 3, v4
	v_mul_lo_u32 v153, v2, s52
	v_add_u32_e32 v155, v1, v153
	v_add_u32_e32 v1, 0x4000, v155
	s_waitcnt vmcnt(4)
	ds_write2_b64 v1, v[128:129], v[130:131] offset0:128 offset1:130
	v_add_u32_e32 v1, v42, v154
	s_waitcnt lgkmcnt(0)
	s_barrier
; DI void attn_s(const unsigned char* sK, int tt, int qb, int qs, int sub, int l31, int h,
;                const bf16x8 (&qf)[4], f32x16 (&O)[4], float& m, float& l, bf16x8 (&pb)[4]) {
;     ...
;         for (int i = 0; i < 4; ++i) st[i & 1] = MFMA32(ka[i], qf[i >> 1], st[i & 1]);
;         __builtin_amdgcn_sched_barrier(0);
; #pragma unroll
;         for (int i = 0; i < 4; ++i) st[i & 1] = MFMA32(kc[i], qf[2 + (i >> 1)], st[i & 1]);
;     }
;     if (tt == 0) {
; #pragma unroll
;         for (int i = 0; i < 16; ++i) { st[0][i] = -INFINITY; if (i < 8) st[1][i] = -INFINITY; }
;     } else if (tt >= 2 * qb + 1) {
;         const int kbase = (tt - 1) * 64 + 4 * h;
; #pragma unroll
;         for (int k2 = 0; k2 < 2; ++k2)
; #pragma unroll
;             for (int i = 0; i < 16; ++i) {
;                 const int key = kbase + k2 * 32 + (i & 3) + 8 * (i >> 2);
;                 if (key > qs) st[k2][i] = -INFINITY;
;             }
;     }
;     float mx;
;     {
;         float t[11];
; #pragma unroll
;         for (int i = 0; i < 5; ++i) t[i] = max3f(st[0][3 * i], st[0][3 * i + 1], st[0][3 * i + 2]);
; #pragma unroll
;         for (int i = 0; i < 5; ++i) t[5 + i] = max3f(st[1][3 * i], st[1][3 * i + 1], st[1][3 * i + 2]);
;         t[10] = fmaxf(st[0][15], st[1][15]);
;         const float u0 = max3f(t[0], t[1], t[2]), u1 = max3f(t[3], t[4], t[5]), u2 = max3f(t[6], t[7], t[8]);
;         mx = max3f(max3f(u0, u1, u2), t[9], t[10]);
;     }
;     mx = xor32_max(mx);
;     if (tt == 0 || __builtin_amdgcn_ballot_w64(mx > 8.0f) != 0ull) {
;         const float delta = tt == 0 ? mx : fmaxf(mx, 0.f);
;         const float alpha = __builtin_amdgcn_exp2f(-delta);
;         m += delta;
;         l *= alpha;
; #pragma unroll
;         for (int d = 0; d < 4; ++d) O[d] = O[d] * alpha;
; #pragma unroll
;         for (int k2 = 0; k2 < 2; ++k2) st[k2] = st[k2] - delta;
;     }
; #pragma unroll
;     for (int k2 = 0; k2 < 2; ++k2)
; #pragma unroll
;         for (int i = 0; i < 16; ++i) st[k2][i] = __builtin_amdgcn_exp2f(st[k2][i]);
;     {
;         const f32x16 sv = st[0] + st[1];
;         const float ps = (((sv[0] + sv[1]) + (sv[2] + sv[3])) + ((sv[4] + sv[5]) + (sv[6] + sv[7]))) + (((sv[8] + sv[9]) + (sv[10] + sv[11])) + ((sv[12] + sv[13]) + (sv[14] + sv[15])));
;         l += ps;
;     }
; #pragma unroll
;     for (int k4 = 0; k4 < 4; ++k4) {
	ds_read_b128 v[26:29], v1 offset:8704
	ds_read_b128 v[30:33], v1 offset:8736
	ds_read_b128 v[34:37], v1 offset:8768
	ds_read_b128 v[38:41], v1 offset:8800
	v_mov_b32_e32 v10, v0
	v_mov_b32_e32 v11, v0
	v_mov_b32_e32 v12, v0
	v_mov_b32_e32 v13, v0
	v_mov_b32_e32 v14, v0
	v_mov_b32_e32 v15, v0
	v_mov_b32_e32 v1, v0
	v_mov_b32_e32 v2, v0
	v_mov_b32_e32 v3, v0
	v_mov_b32_e32 v4, v0
	v_mov_b32_e32 v5, v0
	v_mov_b32_e32 v6, v0
	v_mov_b32_e32 v7, v0
	v_mov_b32_e32 v8, v0
	v_mov_b32_e32 v9, v0
	v_mov_b64_e32 v[24:25], v[14:15]
	v_mov_b64_e32 v[22:23], v[12:13]
	v_mov_b64_e32 v[20:21], v[10:11]
	v_mov_b64_e32 v[18:19], v[8:9]
	v_mov_b64_e32 v[16:17], v[6:7]
	v_mov_b64_e32 v[14:15], v[4:5]
	v_mov_b64_e32 v[12:13], v[2:3]
	v_mov_b64_e32 v[10:11], v[0:1]
	s_waitcnt lgkmcnt(3)
	s_nop 0
	v_mfma_f32_32x32x16_bf16 v[10:25], v[26:29], v[100:103], v[10:25]
	s_waitcnt lgkmcnt(2)
	v_mfma_f32_32x32x16_bf16 v[10:25], v[30:33], v[104:107], v[10:25]
	s_waitcnt lgkmcnt(1)
	v_mfma_f32_32x32x16_bf16 v[10:25], v[34:37], v[108:111], v[10:25]
	v_max3_f32 v1, v188, v188, v188
	s_nop 0
	v_max3_f32 v2, v1, v1, v1
	s_waitcnt lgkmcnt(0)
	v_mfma_f32_32x32x16_bf16 v[10:25], v[38:41], v[112:115], v[10:25]
	v_max3_f32 v3, v188, v188, v18
	v_max3_f32 v4, v19, v20, v21
	v_max3_f32 v5, v22, v23, v24
	s_nop 0
	v_max3_f32 v1, v1, v3, v4
	s_nop 10
	v_max_f32_e32 v6, v25, v25
	v_max3_f32 v1, v2, v2, v1
	v_max_f32_e32 v6, 0xff800000, v6
	v_max3_f32 v1, v1, v5, v6
	s_nop 0
	v_mov_b32_e32 v2, v1
	s_nop 1
	v_permlane32_swap_b32_e32 v1, v2
	v_max_f32_e32 v2, v2, v2
	v_max_f32_e32 v1, v1, v1
	v_max_f32_e32 v86, v1, v2
	v_sub_f32_e32 v1, 0xff800000, v86
	v_sub_f32_e32 v19, v19, v86
	v_sub_f32_e32 v26, v18, v86
	v_sub_f32_e32 v21, v21, v86
	v_sub_f32_e32 v20, v20, v86
	v_exp_f32_e32 v18, v1
	v_exp_f32_e32 v26, v26
	v_exp_f32_e32 v27, v19
	v_sub_f32_e32 v23, v23, v86
	v_sub_f32_e32 v22, v22, v86
	v_exp_f32_e32 v28, v20
	v_exp_f32_e32 v29, v21
	v_sub_f32_e32 v25, v25, v86
	v_sub_f32_e32 v24, v24, v86
	v_exp_f32_e32 v30, v22
	v_exp_f32_e32 v31, v23
	v_exp_f32_e32 v32, v24
	v_exp_f32_e32 v33, v25
	v_pk_add_f32 v[34:35], v[18:19], v[26:27] op_sel_hi:[0,1]
	v_add_f32_e32 v36, v18, v18
	v_pk_add_f32 v[24:25], v[18:19], v[28:29] op_sel_hi:[0,1]
	v_mov_b32_e32 v37, v34
	v_mov_b32_e32 v34, v36
	v_pk_add_f32 v[22:23], v[18:19], v[30:31] op_sel_hi:[0,1]
	v_pk_add_f32 v[34:35], v[36:37], v[34:35]
	v_mov_b32_e32 v37, v24
	v_mov_b32_e32 v24, v36
	v_pk_add_f32 v[20:21], v[18:19], v[32:33] op_sel_hi:[0,1]
	v_pk_add_f32 v[24:25], v[36:37], v[24:25]
	v_mov_b32_e32 v37, v22
	v_mov_b32_e32 v22, v36
	v_pk_add_f32 v[22:23], v[36:37], v[22:23]
	v_mov_b32_e32 v37, v20
	v_mov_b32_e32 v20, v36
	v_pk_add_f32 v[20:21], v[36:37], v[20:21]
	v_cvt_pk_bf16_f32 v88, v18, v18
	v_lshlrev_b32_e32 v18, 7, v146
	v_pk_add_f32 v[24:25], v[34:35], v[24:25]
	v_pk_add_f32 v[20:21], v[22:23], v[20:21]
	v_sub_u32_e32 v18, v42, v18
	v_pk_add_f32 v[20:21], v[24:25], v[20:21]
	v_add_u32_e32 v185, v18, v98
	v_add_f32_e32 v1, v20, v21
	ds_read_b128 v[18:21], v185 offset:17408
	ds_read_b128 v[22:25], v185 offset:22016
	ds_read_b128 v[92:95], v185 offset:26624
	ds_read_b128 v[142:145], v185 offset:31232
	v_exp_f32_e64 v184, -v86
	v_mov_b32_e32 v89, v88
	v_mov_b32_e32 v90, v88
	v_mov_b32_e32 v91, v88
	v_mul_f32_e32 v2, 0, v184
	v_mov_b32_e32 v3, v2
	v_mov_b32_e32 v4, v2
	v_mov_b32_e32 v5, v2
	v_mov_b32_e32 v6, v2
	v_mov_b32_e32 v7, v2
	v_mov_b32_e32 v8, v2
	v_mov_b32_e32 v9, v2
	v_mov_b32_e32 v10, v2
	v_mov_b32_e32 v11, v2
	v_mov_b32_e32 v12, v2
	v_mov_b32_e32 v13, v2
	v_mov_b32_e32 v14, v2
	v_mov_b32_e32 v15, v2
	v_mov_b32_e32 v16, v2
	v_mov_b32_e32 v17, v2
	v_cvt_pk_bf16_f32 v156, v26, v27
	v_cvt_pk_bf16_f32 v157, v28, v29
	v_cvt_pk_bf16_f32 v158, v30, v31
	v_cvt_pk_bf16_f32 v159, v32, v33
	ds_read_b128 v[160:163], v185 offset:17440
	ds_read_b128 v[164:167], v185 offset:22048
	ds_read_b128 v[168:171], v185 offset:26656
	ds_read_b128 v[172:175], v185 offset:31264
	s_waitcnt lgkmcnt(7)
	v_mfma_f32_32x32x16_bf16 v[50:65], v[18:21], v[88:91], v[2:17]
	s_waitcnt lgkmcnt(6)
	v_mfma_f32_32x32x16_bf16 v[34:49], v[22:25], v[88:91], v[2:17]
	s_waitcnt lgkmcnt(5)
	v_mfma_f32_32x32x16_bf16 v[18:33], v[92:95], v[88:91], v[2:17]
	s_waitcnt lgkmcnt(4)
	v_mfma_f32_32x32x16_bf16 v[2:17], v[142:145], v[88:91], v[2:17]
	ds_read_b128 v[92:95], v185 offset:17472
	ds_read_b128 v[142:145], v185 offset:22080
	ds_read_b128 v[176:179], v185 offset:26688
	ds_read_b128 v[180:183], v185 offset:31296
	s_waitcnt lgkmcnt(7)
	v_mfma_f32_32x32x16_bf16 v[50:65], v[160:163], v[88:91], v[50:65]
	s_waitcnt lgkmcnt(6)
	v_mfma_f32_32x32x16_bf16 v[34:49], v[164:167], v[88:91], v[34:49]
	s_waitcnt lgkmcnt(5)
	v_mfma_f32_32x32x16_bf16 v[18:33], v[168:171], v[88:91], v[18:33]
	s_waitcnt lgkmcnt(4)
	v_mfma_f32_32x32x16_bf16 v[2:17], v[172:175], v[88:91], v[2:17]
	ds_read_b128 v[160:163], v185 offset:17504
	ds_read_b128 v[164:167], v185 offset:22112
	ds_read_b128 v[168:171], v185 offset:26720
	ds_read_b128 v[172:175], v185 offset:31328
	s_waitcnt lgkmcnt(7)
	v_mfma_f32_32x32x16_bf16 v[50:65], v[92:95], v[88:91], v[50:65]
	s_waitcnt lgkmcnt(6)
	v_mfma_f32_32x32x16_bf16 v[34:49], v[142:145], v[88:91], v[34:49]
	s_waitcnt lgkmcnt(5)
	v_mfma_f32_32x32x16_bf16 v[18:33], v[176:179], v[88:91], v[18:33]
	s_waitcnt lgkmcnt(4)
	v_mfma_f32_32x32x16_bf16 v[2:17], v[180:183], v[88:91], v[2:17]
	s_waitcnt lgkmcnt(3)
	v_mfma_f32_32x32x16_bf16 v[50:65], v[160:163], v[156:159], v[50:65]
	s_waitcnt vmcnt(3)
	ds_write_b128 v87, v[74:77] offset:35840
	s_waitcnt vmcnt(1)
	ds_write_b128 v96, v[78:81] offset:35840
	v_add_u32_e32 v74, 0xd000, v97
	ds_write2_b64 v74, v[70:71], v[72:73] offset1:2
	v_add_u32_e32 v70, 0xd000, v155
	v_fmac_f32_e32 v1, 0, v184
	s_cmpk_gt_u32 s4, 0x7f
	s_waitcnt vmcnt(0)
	ds_write2_b64 v70, v[66:67], v[68:69] offset1:2
	s_waitcnt lgkmcnt(6)
	v_mfma_f32_32x32x16_bf16 v[34:49], v[164:167], v[156:159], v[34:49]
	s_waitcnt lgkmcnt(0)
	s_barrier
; DI void attn_s(const unsigned char* sK, int tt, int qb, int qs, int sub, int l31, int h,
;                const bf16x8 (&qf)[4], f32x16 (&O)[4], float& m, float& l, bf16x8 (&pb)[4]) {
;     ...
;     for (int k2 = 0; k2 < 2; ++k2)
; #pragma unroll
;         for (int i = 0; i < 16; ++i) st[k2][i] = -m;
; DI void attn_item(const Params& p, unsigned char* lds, int b, int hd, int qb, float lam) {
;     ...
;     for (int tt = 1; tt < T; ++tt) {
;         if (tt + 1 < T) A_LOAD_REAL(k0r, v0r);
;         attn_s(lds + bc * A_STAGE, tt, qb, qs, sub, l31, h, qf, O, m, l, pb);
	v_mfma_f32_32x32x16_bf16 v[18:33], v[168:171], v[156:159], v[18:33]
	v_mfma_f32_32x32x16_bf16 v[2:17], v[172:175], v[156:159], v[2:17]
	s_cbranch_scc1 .LBB0_1824
	s_lshr_b32 s4, s4, 1
	s_lshl_b32 s5, s5, 1
	s_and_b32 s4, s4, 0x7ffffff8
	s_lshl_b32 s0, s0, 1
	s_or_b32 s4, s5, s4
	v_mul_u32_u24_e32 v155, 0x110, v146
	v_mul_u32_u24_e32 v156, 0x90, v146
	s_mov_b32 s13, 1
	s_add_i32 s6, s0, 3
	v_lshl_add_u64 v[142:143], v[84:85], 0, s[88:89]
	v_lshl_add_u64 v[142:143], v[142:143], 0, s[88:89]
	v_add_f32_e32 v157, 0, v86
	v_lshl_add_u64 v[144:145], v[82:83], 0, s[90:91]
	v_lshl_add_u64 v[144:145], v[144:145], 0, s[90:91]
	s_mov_b32 s7, 2
	v_lshl_or_b32 v158, v149, 2, 59
	s_sub_i32 s11, 0, s4
	s_movk_i32 s12, 0xffc0
	v_xor_b32_e32 v240, 0x80000000, v157
	v_mov_b32_e32 v241, v240
	v_mov_b32_e32 v242, v240
	v_mov_b32_e32 v243, v240
	v_mov_b32_e32 v244, v240
	v_mov_b32_e32 v245, v240
	v_mov_b32_e32 v246, v240
	v_mov_b32_e32 v247, v240
	v_mov_b32_e32 v248, v240
	v_mov_b32_e32 v249, v240
	v_mov_b32_e32 v250, v240
	v_mov_b32_e32 v251, v240
	v_mov_b32_e32 v252, v240
	v_mov_b32_e32 v253, v240
	v_mov_b32_e32 v254, v240
	v_mov_b32_e32 v255, v240
	v_readfirstlane_b32 s99, v147
	s_cmp_eq_u32 s99, 1
	s_cbranch_scc0 .Lpipe_nooffs
	s_barrier
